# DeltaNet conv stage: conv weights of the wave's three outer iterations loaded before the loop (rotated in registers), so an iteration no longer waits vmcnt(0) for its predecessor's stores and a weight
# speedup vs baseline: 1.0087x; 1.0087x over previous
; #define LAS __attribute__((address_space(3)))
; __device__ __forceinline__ void mixer_pre_item(int item, const float* const* in, int l, unsigned char* ws, LAS unsigned char* lds, int tid, int lane, int wave) {
;     ...
;     __syncthreads();
; #pragma unroll
;     for (int i = 0; i < 9; ++i) { const int id = tid + 512 * i;
;         if (id < 35 * 128) { const int row = id >> 7, pc = id & 127, s = s0 - 3 + row;
;             u32x4v v = (u32x4v){0u, 0u, 0u, 0u};
;             if (s >= 0) v = *(const u32x4v*)(U + ((size_t)b * SEQ + s) * NIN + (pc < 32 ? pc * 8 : U_DQ + (pc - 32) * 8));
;             if (pc < 32) *(LAS u32x4v*)(STGL + row * 256 + pc * 8) = v; else *(LAS u32x4v*)(STGD + row * 768 + (pc - 32) * 8) = v; } }
;     __syncthreads();
;     for (int task = wave; task < 24; task += 8) {
;         const int g = task >> 1, t0 = (task & 1) * 16, kind = g >> 2, hh = g & 3, cc = g * 64 + lane;
;         const float* cw = in[17] + (size_t)l * 4 * 768;
;         const float w0 = cw[cc], w1 = cw[768 + cc], w2 = cw[1536 + cc], w3 = cw[2304 + cc];
.LBB0_567:
	v_mov_b32_e32 v34, v166
	s_ashr_i32 s18, s14, 6
	v_and_b32_e32 v2, 0x7f, v34
	v_lshlrev_b32_e32 v0, 3, v2
	v_or_b32_e32 v3, 0x400, v0
	v_cmp_gt_u32_e64 s[40:41], 32, v2
	s_lshl_b32 s9, s14, 5
	v_readlane_b32 s34, v251, 4
	v_cndmask_b32_e64 v0, v3, v0, s[40:41]
	s_and_b32 s30, s9, 0x7e0
	s_ashr_i32 s19, s18, 31
	v_lshlrev_b32_e32 v0, 1, v0
	v_readlane_b32 s35, v251, 5
	s_movk_i32 s31, 0x1180
	v_readfirstlane_b32 s15, v34
	s_lshl_b64 s[20:21], s[18:19], 11
	s_add_i32 s9, s30, -3
	v_cmp_lt_u32_e32 vcc, 31, v2
	v_lshl_add_u64 v[8:9], s[34:35], 0, v[0:1]
	v_lshl_add_u32 v6, v2, 4, 0
	v_cmp_gt_i32_e64 s[40:41], s31, v34
	s_barrier
	v_ashrrev_i32_e32 v7, 7, v34
	v_add_u32_e32 v0, s9, v7
	v_mov_b32_e32 v40, 0
	v_mov_b32_e32 v41, 0
	v_mov_b32_e32 v42, 0
	v_mov_b32_e32 v43, 0
	v_cmp_lt_i32_e64 s[40:41], -1, v0
	s_and_saveexec_b64 s[42:43], s[40:41]
	v_lshl_add_u64 v[2:3], s[20:21], 0, v[0:1]
	v_mad_u64_u32 v[4:5], s[34:35], v2, s36, v[8:9]
	v_mad_i32_i24 v5, v3, s36, v5
	global_load_dwordx4 v[40:43], v[4:5], off
	s_or_b64 exec, exec, s[42:43]
	v_add_u32_e32 v0, 4, v0
	v_lshl_add_u64 v[2:3], s[20:21], 0, v[0:1]
	v_mad_u64_u32 v[4:5], s[34:35], v2, s36, v[8:9]
	v_mad_i32_i24 v5, v3, s36, v5
	s_mov_b64 s[42:43], 0x5000
	global_load_dwordx4 v[44:47], v[4:5], off
	v_lshl_add_u64 v[4:5], v[4:5], 0, s[42:43]
	global_load_dwordx4 v[48:51], v[4:5], off
	v_lshl_add_u64 v[4:5], v[4:5], 0, s[42:43]
	global_load_dwordx4 v[52:55], v[4:5], off
	v_lshl_add_u64 v[4:5], v[4:5], 0, s[42:43]
	global_load_dwordx4 v[56:59], v[4:5], off
	v_lshl_add_u64 v[4:5], v[4:5], 0, s[42:43]
	global_load_dwordx4 v[60:63], v[4:5], off
	v_lshl_add_u64 v[4:5], v[4:5], 0, s[42:43]
	global_load_dwordx4 v[64:67], v[4:5], off
	v_lshl_add_u64 v[4:5], v[4:5], 0, s[42:43]
	global_load_dwordx4 v[68:71], v[4:5], off
	v_lshl_add_u64 v[4:5], v[4:5], 0, s[42:43]
	s_movk_i32 s31, 0x180
	v_cmp_gt_i32_e64 s[40:41], s31, v34
	s_and_saveexec_b64 s[38:39], s[40:41]
	global_load_dwordx4 v[72:75], v[4:5], off
	s_or_b64 exec, exec, s[38:39]
	v_lshl_add_u32 v10, v7, 9, v6
	s_movk_i32 s31, 0x600
	v_mad_u32_u24 v11, v7, s31, v6
	v_add_u32_e32 v11, 0x4400, v11
	v_mov_b32_e32 v2, 0x800
	v_mov_b32_e32 v3, 0x1800
	v_cndmask_b32_e32 v10, v10, v11, vcc
	v_cndmask_b32_e32 v11, v2, v3, vcc
	s_waitcnt vmcnt(7)
	ds_write_b128 v10, v[40:43]
	v_add_u32_e32 v10, v10, v11
	s_waitcnt vmcnt(6)
	ds_write_b128 v10, v[44:47]
	v_add_u32_e32 v10, v10, v11
	s_waitcnt vmcnt(5)
	ds_write_b128 v10, v[48:51]
	v_add_u32_e32 v10, v10, v11
	s_waitcnt vmcnt(4)
	ds_write_b128 v10, v[52:55]
	v_add_u32_e32 v10, v10, v11
	s_waitcnt vmcnt(3)
	ds_write_b128 v10, v[56:59]
	v_add_u32_e32 v10, v10, v11
	s_waitcnt vmcnt(2)
	ds_write_b128 v10, v[60:63]
	v_add_u32_e32 v10, v10, v11
	s_waitcnt vmcnt(1)
	ds_write_b128 v10, v[64:67]
	v_add_u32_e32 v10, v10, v11
	s_waitcnt vmcnt(0)
	ds_write_b128 v10, v[68:71]
	v_add_u32_e32 v10, v10, v11
	s_waitcnt vmcnt(0)
	s_and_saveexec_b64 s[38:39], s[40:41]
	ds_write_b128 v10, v[72:75]
	s_or_b64 exec, exec, s[38:39]
	s_bfe_u32 s9, s8, 0x60005
	s_ashr_i32 s31, s15, 6
	v_and_b32_e32 v35, 63, v34
	s_cmp_lt_i32 s31, 24
	s_waitcnt lgkmcnt(0)
	s_barrier
	s_cbranch_scc0 .LBB0_633
	v_lshlrev_b32_e32 v0, 1, v35
	v_readlane_b32 s33, v248, 48
	s_lshl_b32 s35, s9, 5
	s_lshl_b32 s34, s31, 5
	v_add_u32_e32 v18, s33, v0
	s_lshl_b32 s33, s31, 4
	v_readlane_b32 s38, v249, 59
	v_readlane_b32 s39, v249, 60
	s_add_u32 s35, s20, s35
	s_addc_u32 s42, s21, 0
	s_waitcnt vmcnt(0)
	v_lshl_add_u64 v[2:3], s[38:39], 0, v[0:1]
	s_lshl_b32 s100, s31, 5
	s_andn2_b32 s100, s100, 63
	v_or_b32_e32 v144, s100, v35
	v_ashrrev_i32_e32 v145, 31, v144
	v_lshl_add_u64 v[144:145], v[144:145], 2, s[10:11]
	s_mov_b64 s[100:101], 0x400
	global_load_dword v148, v[144:145], off
	global_load_dword v149, v[144:145], off offset:3072
	v_add_co_u32_e32 v146, vcc, s37, v144
	s_nop 1
	v_addc_co_u32_e32 v147, vcc, 0, v145, vcc
	global_load_dword v150, v[146:147], off offset:2048
	v_add_co_u32_e32 v146, vcc, s77, v144
	s_nop 1
	v_addc_co_u32_e32 v147, vcc, 0, v145, vcc
	global_load_dword v151, v[146:147], off offset:1024
	v_lshl_add_u64 v[144:145], v[144:145], 0, s[100:101]
	global_load_dword v152, v[144:145], off
	global_load_dword v153, v[144:145], off offset:3072
	v_add_co_u32_e32 v146, vcc, s37, v144
	s_nop 1
	v_addc_co_u32_e32 v147, vcc, 0, v145, vcc
	global_load_dword v154, v[146:147], off offset:2048
	v_add_co_u32_e32 v146, vcc, s77, v144
	s_nop 1
	v_addc_co_u32_e32 v147, vcc, 0, v145, vcc
	global_load_dword v155, v[146:147], off offset:1024
	v_lshl_add_u64 v[144:145], v[144:145], 0, s[100:101]
	global_load_dword v168, v[144:145], off
	global_load_dword v169, v[144:145], off offset:3072
	v_add_co_u32_e32 v146, vcc, s37, v144
	s_nop 1
	v_addc_co_u32_e32 v147, vcc, 0, v145, vcc
	global_load_dword v170, v[146:147], off offset:2048
	v_add_co_u32_e32 v146, vcc, s77, v144
	s_nop 1
	v_addc_co_u32_e32 v147, vcc, 0, v145, vcc
	global_load_dword v171, v[146:147], off offset:1024
	s_waitcnt vmcnt(8)
	s_branch .LBB0_615
; __device__ __forceinline__ float bf2f(unsigned short b) { return __uint_as_float(((unsigned)b) << 16); }
; __device__ __forceinline__ void mixer_pre_item(int item, const float* const* in, int l, unsigned char* ws, LAS unsigned char* lds, int tid, int lane, int wave) {
;     ...
;     for (int task = wave; task < 24; task += 8) {
;         const int g = task >> 1, t0 = (task & 1) * 16, kind = g >> 2, hh = g & 3, cc = g * 64 + lane;
;         const float* cw = in[17] + (size_t)l * 4 * 768;
;         const float w0 = cw[cc], w1 = cw[768 + cc], w2 = cw[1536 + cc], w3 = cw[2304 + cc];
;         bf16_t* dst = (bf16_t*)(ws + WS_R2 + (kind == 0 ? R2_DQ : kind == 1 ? R2_DK : R2_DV)) + (g0 + t0) * 256 + hh * 64 + lane;
;         float xm3 = bf2f(STGD[t0 * 768 + cc]), xm2 = bf2f(STGD[(t0 + 1) * 768 + cc]), xm1 = bf2f(STGD[(t0 + 2) * 768 + cc]);
.LBB0_614:
	s_waitcnt vmcnt(16)
	v_mov_b32_e32 v148, v152
	v_mov_b32_e32 v149, v153
	v_mov_b32_e32 v150, v154
	v_mov_b32_e32 v151, v155
	v_mov_b32_e32 v152, v168
	v_mov_b32_e32 v153, v169
	v_mov_b32_e32 v154, v170
	v_mov_b32_e32 v155, v171
	s_add_i32 s38, s31, 8
	s_addk_i32 s33, 0x80
	s_addk_i32 s34, 0x100
	s_cmp_gt_i32 s31, 15
	s_mov_b32 s31, s38
	s_cbranch_scc1 .LBB0_633
.LBB0_615:
	s_bfe_u32 s38, s33, 0x10004
	s_lshl_b32 s43, s34, 1
	s_mul_i32 s39, s38, 0x6000
	s_and_b32 s40, s43, 0xffffff80
	s_add_i32 s44, s39, s40
	s_lshl_b32 s38, s38, 4
	s_add_u32 s38, s35, s38
	s_addc_u32 s39, s42, 0
	s_lshl_b32 s40, s31, 5
	s_andn2_b32 s40, s40, 63
	v_or_b32_e32 v8, s40, v35
	v_ashrrev_i32_e32 v9, 31, v8
	v_lshl_add_u64 v[6:7], v[8:9], 2, s[10:11]
	v_add_co_u32_e32 v10, vcc, s37, v6
	s_lshl_b64 s[40:41], s[38:39], 9
	s_nop 0
	v_addc_co_u32_e32 v11, vcc, 0, v7, vcc
	v_add_co_u32_e32 v12, vcc, s77, v6
	s_lshl_b32 s38, s31, 4
	s_nop 0
	v_addc_co_u32_e32 v13, vcc, 0, v7, vcc
	s_nop 0
	s_and_b32 s45, s43, 0x180
	s_and_b32 s43, s38, 16
	s_ashr_i32 s48, s31, 3
	s_cmp_eq_u32 s48, 1
	s_mov_b32 s38, 0x3200000
	s_cselect_b32 s49, s38, 0x4200000
	s_cmp_lt_u32 s31, 8
	s_cselect_b64 vcc, -1, 0
	s_and_b64 s[38:39], vcc, exec
	s_mulk_i32 s43, 0x600
	s_cselect_b32 s49, 0x2200000, s49
	s_add_i32 s38, s43, 0
	v_lshl_add_u32 v8, v8, 1, s38
	ds_read_u16 v9, v8 offset:17920
	ds_read_u16 v11, v8 offset:19456
	ds_read_u16 v8, v8 offset:20992
	s_cmp_lt_i32 s48, 2
	s_cselect_b64 s[38:39], -1, 0
	s_add_u32 s40, s49, s40
	s_addc_u32 s41, 0, s41
	s_or_b32 s40, s40, s45
	v_cndmask_b32_e32 v0, 1.0, v231, vcc
	v_add_u32_e32 v19, s44, v18
	s_mov_b32 s43, 0
	s_waitcnt lgkmcnt(2)
	v_lshlrev_b32_e32 v10, 16, v9
	s_waitcnt lgkmcnt(1)
	v_lshlrev_b32_e32 v13, 16, v11
	s_waitcnt lgkmcnt(0)
	v_lshlrev_b32_e32 v12, 16, v8
	v_lshl_add_u64 v[8:9], v[2:3], 0, s[40:41]
	v_mov_b32_e32 v5, v148
	v_mov_b32_e32 v4, v149
	v_mov_b32_e32 v6, v150
	v_mov_b32_e32 v7, v151
	v_mov_b32_e32 v116, v10
	v_mov_b32_e32 v117, v13
	v_mov_b32_e32 v118, v13
	v_mov_b32_e32 v119, v12
	v_mov_b32_e32 v134, 0xbfb8aa3b
	v_mov_b32_e32 v136, 1.0
